# DSA attention: QK^T K-fragment ds_reads software-pipelined 4 deep through dead VGPRs (was one read per MFMA with lgkmcnt(0))
# speedup vs baseline: 1.0000x; 1.0000x over previous
; #define LAS __attribute__((address_space(3)))
; DEVI int crow(int r, int hi) { return (r & 3) + 8 * (r >> 2) + 4 * hi; }
; DEVI float xlane32(float v) { return __shfl_xor(v, 32); }
; DEVI float max3f(float a, float b, float c) { float r; asm("v_max3_f32 %0, %1, %2, %3" : "=v"(r) : "v"(a), "v"(b), "v"(c)); return r; }
; DEVI void qkt(f32x16& p0, f32x16& p1, LAS const unsigned char* Ks, const bf16x8* qr, int r32, int hi) {
;     p0 = (f32x16){0.f, 0.f, 0.f, 0.f, 0.f, 0.f, 0.f, 0.f, 0.f, 0.f, 0.f, 0.f, 0.f, 0.f, 0.f, 0.f}; p1 = p0;
; #pragma unroll
;     for (int d0 = 0; d0 < 8; ++d0) { const int cb = (d0 * 16 + hi * 8) * 2;
;         const bf16x8 b0 = *(LAS const bf16x8*)(Ks + FA_KSWZ(r32, cb));
;         const bf16x8 b1 = *(LAS const bf16x8*)(Ks + FA_KSWZ(32 + r32, cb));
;         p0 = __builtin_amdgcn_mfma_f32_32x32x16_bf16(b0, qr[d0], p0, 0, 0, 0);
;         p1 = __builtin_amdgcn_mfma_f32_32x32x16_bf16(b1, qr[d0], p1, 0, 0, 0); }
; template <int MODE>
; DEVI void attn_unit(LAS unsigned char* lds, const bf16_t* Qw, int ldq, const bf16_t* Kb, const bf16_t* Vb, int ldk, bf16_t* Ow, int ldo,
;                     int j_first, int ntiles, int jstep, int wj_lo, int wj_hi, int t0) {
;     ...
;                 float pmax = fmaxf(p0[0], p1[0]);
; #pragma unroll
;                 for (int r = 1; r < 15; r += 2) pmax = max3f(pmax, p0[r], p0[r + 1]);
; #pragma unroll
;                 for (int r = 1; r < 15; r += 2) pmax = max3f(pmax, p1[r], p1[r + 1]);
;                 pmax = max3f(pmax, p0[15], p1[15]);
;                 pmax = fmaxf(pmax, xlane32(pmax));
;                 const float pm2 = (MODE == M_BAND) ? pmax : pmax * C2;
;                 float mn = m_reg;
;                 if (!__all(pm2 - m_reg <= 8.f)) {
;                     mn = fmaxf(m_reg, pm2); const float alpha = __builtin_amdgcn_exp2f(m_reg - mn); m_reg = mn; l_reg *= alpha;
;                     if (hi == 0) al_l[r32] = alpha; asm volatile("s_waitcnt lgkmcnt(0)" ::: "memory");
; #pragma unroll
;                     for (int r = 0; r < 16; ++r) { const float af = al_l[crow(r, hi)];
; #pragma unroll
;                         for (int d = 0; d < 4; ++d) o[d][r] *= af; }
.LBB11_1656:
	v_add_u32_e32 v184, s4, v175
	s_waitcnt lgkmcnt(0)
	s_barrier
	v_and_b32_e32 v186, 64, v215
	v_add_u32_e32 v186, 64, v186
	s_mov_b32 s4, 0x41000000
	v_add_u32_e32 v185, v184, v176
	ds_read_b128 v[220:223], v185 offset:32768
	ds_read_b128 v[224:227], v185 offset:40960
	v_add_u32_e32 v236, v184, v177
	ds_read_b128 v[228:231], v236 offset:32768
	ds_read_b128 v[232:235], v236 offset:40960
	s_waitcnt lgkmcnt(3)
	v_mfma_f32_32x32x16_bf16 v[68:83], v[220:223], v[100:103], 0
	v_add_u32_e32 v237, v184, v178
	ds_read_b128 v[220:223], v237 offset:32768
	s_waitcnt lgkmcnt(3)
	v_mfma_f32_32x32x16_bf16 v[84:99], v[224:227], v[100:103], 0
	ds_read_b128 v[224:227], v237 offset:40960
	s_waitcnt lgkmcnt(3)
	v_mfma_f32_32x32x16_bf16 v[68:83], v[228:231], v[104:107], v[68:83]
	v_add_u32_e32 v238, v184, v179
	ds_read_b128 v[228:231], v238 offset:32768
	s_waitcnt lgkmcnt(3)
	v_mfma_f32_32x32x16_bf16 v[84:99], v[232:235], v[104:107], v[84:99]
	ds_read_b128 v[232:235], v238 offset:40960
	s_waitcnt lgkmcnt(3)
	v_mfma_f32_32x32x16_bf16 v[68:83], v[220:223], v[108:111], v[68:83]
	v_add_u32_e32 v185, v184, v181
	ds_read_b128 v[220:223], v185 offset:32768
	s_waitcnt lgkmcnt(3)
	v_mfma_f32_32x32x16_bf16 v[84:99], v[224:227], v[108:111], v[84:99]
	ds_read_b128 v[224:227], v185 offset:40960
	s_waitcnt lgkmcnt(3)
	v_mfma_f32_32x32x16_bf16 v[68:83], v[228:231], v[112:115], v[68:83]
	v_add_u32_e32 v236, v184, v183
	ds_read_b128 v[228:231], v236 offset:32768
	s_waitcnt lgkmcnt(3)
	v_mfma_f32_32x32x16_bf16 v[84:99], v[232:235], v[112:115], v[84:99]
	ds_read_b128 v[232:235], v236 offset:40960
	s_waitcnt lgkmcnt(3)
	v_mfma_f32_32x32x16_bf16 v[68:83], v[220:223], v[116:119], v[68:83]
	v_add_u32_e32 v237, v184, v198
	ds_read_b128 v[220:223], v237 offset:32768
	s_waitcnt lgkmcnt(3)
	v_mfma_f32_32x32x16_bf16 v[84:99], v[224:227], v[116:119], v[84:99]
	ds_read_b128 v[224:227], v237 offset:40960
	s_waitcnt lgkmcnt(3)
	v_mfma_f32_32x32x16_bf16 v[68:83], v[228:231], v[120:123], v[68:83]
	v_add_u32_e32 v238, v184, v199
	ds_read_b128 v[228:231], v238 offset:40960
	s_waitcnt lgkmcnt(3)
	v_mfma_f32_32x32x16_bf16 v[84:99], v[232:235], v[120:123], v[84:99]
	ds_read_b128 v[232:235], v238 offset:32768
	s_waitcnt lgkmcnt(3)
	v_mfma_f32_32x32x16_bf16 v[68:83], v[220:223], v[124:127], v[68:83]
	s_waitcnt lgkmcnt(2)
	v_mfma_f32_32x32x16_bf16 v[84:99], v[224:227], v[124:127], v[84:99]
	s_waitcnt lgkmcnt(1)
	v_mfma_f32_32x32x16_bf16 v[84:99], v[228:231], v[128:131], v[84:99]
	s_waitcnt lgkmcnt(0)
	v_mfma_f32_32x32x16_bf16 v[68:83], v[232:235], v[128:131], v[68:83]
	s_nop 8
	v_max_f32_e32 v184, v84, v84
	s_nop 1
	v_max_f32_e32 v185, v68, v68
	v_max_f32_e32 v184, v185, v184
	v_max3_f32 v184, v184, v69, v70
	v_xor_b32_e32 v185, 32, v215
	v_max3_f32 v184, v184, v71, v72
	v_cmp_lt_i32_e32 vcc, v185, v186
	v_max3_f32 v184, v184, v73, v74
	s_nop 0
	v_max3_f32 v184, v184, v75, v76
	s_nop 0
	v_max3_f32 v184, v184, v77, v78
	v_cndmask_b32_e32 v185, v215, v185, vcc
	v_max3_f32 v184, v184, v79, v80
	v_lshlrev_b32_e32 v204, 2, v185
	v_max3_f32 v184, v184, v81, v82
	s_nop 0
	v_max3_f32 v184, v184, v85, v86
	s_nop 0
	v_max3_f32 v184, v184, v87, v88
	s_nop 0
	v_max3_f32 v184, v184, v89, v90
	s_nop 0
	v_max3_f32 v184, v184, v91, v92
	s_nop 0
	v_max3_f32 v184, v184, v93, v94
	s_nop 0
	v_max3_f32 v184, v184, v95, v96
	s_nop 0
	v_max3_f32 v184, v184, v97, v98
	s_nop 0
	v_max3_f32 v184, v184, v83, v99
	ds_bpermute_b32 v185, v204, v184
	v_max_f32_e32 v184, v184, v184
	s_waitcnt lgkmcnt(0)
	v_max_f32_e32 v185, v185, v185
	v_max_f32_e32 v205, v184, v185
	v_fma_f32 v184, v205, s0, -v206
	v_cmp_ge_f32_e32 vcc, s4, v184
	s_cmp_eq_u64 vcc, exec
	s_cbranch_scc1 .LBB11_1660
	v_mul_f32_e32 v184, 0x3e0293ee, v205
	v_max_f32_e32 v184, v184, v184
	v_max_f32_e32 v185, v206, v206
	v_max_f32_e32 v205, v185, v184
	v_sub_f32_e32 v184, v206, v205
	v_exp_f32_e32 v206, v184
	s_and_saveexec_b64 s[4:5], s[40:41]
	ds_write_b32 v180, v206 offset:128
	s_or_b64 exec, exec, s[4:5]
	s_waitcnt lgkmcnt(0)
	v_add_u32_e32 v184, v167, v162
	ds_read_b128 v[220:223], v184 offset:128
	ds_read_b128 v[224:227], v184 offset:160
	ds_read_b128 v[228:231], v184 offset:192
	ds_read_b128 v[232:235], v184 offset:224
	v_mul_f32_e32 v203, v203, v206
	s_waitcnt lgkmcnt(3)
	v_pk_mul_f32 v[6:7], v[6:7], v[222:223]
	s_waitcnt lgkmcnt(2)
	v_pk_mul_f32 v[8:9], v[8:9], v[224:225]
	s_waitcnt lgkmcnt(1)
	v_pk_mul_f32 v[12:13], v[12:13], v[228:229]
	s_waitcnt lgkmcnt(0)
	v_pk_mul_f32 v[16:17], v[16:17], v[232:233]
	v_pk_mul_f32 v[18:19], v[18:19], v[234:235]
	v_pk_mul_f32 v[14:15], v[14:15], v[230:231]
	v_pk_mul_f32 v[10:11], v[10:11], v[226:227]
	v_pk_mul_f32 v[4:5], v[4:5], v[220:221]
	v_pk_mul_f32 v[64:65], v[64:65], v[232:233]
	v_pk_mul_f32 v[60:61], v[60:61], v[228:229]
	v_pk_mul_f32 v[56:57], v[56:57], v[224:225]
	v_pk_mul_f32 v[66:67], v[66:67], v[234:235]
	v_pk_mul_f32 v[62:63], v[62:63], v[230:231]
	v_pk_mul_f32 v[58:59], v[58:59], v[226:227]
	v_pk_mul_f32 v[54:55], v[54:55], v[222:223]
	v_pk_mul_f32 v[52:53], v[52:53], v[220:221]
	v_pk_mul_f32 v[48:49], v[48:49], v[232:233]
	v_pk_mul_f32 v[44:45], v[44:45], v[228:229]
	v_pk_mul_f32 v[40:41], v[40:41], v[224:225]
	v_pk_mul_f32 v[50:51], v[50:51], v[234:235]
	v_pk_mul_f32 v[46:47], v[46:47], v[230:231]
	v_pk_mul_f32 v[42:43], v[42:43], v[226:227]
	v_pk_mul_f32 v[38:39], v[38:39], v[222:223]
	v_pk_mul_f32 v[36:37], v[36:37], v[220:221]
	v_pk_mul_f32 v[32:33], v[32:33], v[232:233]
	v_pk_mul_f32 v[28:29], v[28:29], v[228:229]
	v_pk_mul_f32 v[24:25], v[24:25], v[224:225]
	v_pk_mul_f32 v[34:35], v[34:35], v[234:235]
	v_pk_mul_f32 v[30:31], v[30:31], v[230:231]
	v_pk_mul_f32 v[26:27], v[26:27], v[226:227]
	v_pk_mul_f32 v[22:23], v[22:23], v[222:223]
	v_pk_mul_f32 v[20:21], v[20:21], v[220:221]
	s_branch .LBB11_1661
